# plus: the four post-attention grid barriers become XCD-local (leader skips L2 write-back and cross-XCD rendezvous) when a run-time census shows every blockIdx%8 class sits on one physical XCC; all pro
# speedup vs baseline: 1.0967x; 1.0236x over previous
; #define LAS __attribute__((address_space(3)))
; __device__ __forceinline__ unsigned xb_add(unsigned* p, unsigned v) { return __hip_atomic_fetch_add(p, v, __ATOMIC_RELAXED, __HIP_MEMORY_SCOPE_AGENT); }
; __device__ __forceinline__ unsigned xb_xcc_id() { return (unsigned)__builtin_amdgcn_s_getreg((3 << 11) | 20) & 0xFu; }
; __device__ __forceinline__ XcdBarrier xcd_barrier_post(unsigned* bar, volatile LAS unsigned* st) {
;     XcdBarrier b; b.bar = bar; b.x = xb_xcc_id(); b.st = st;
;     if (threadIdx.x == 0) (void)xb_add(&bar[XB_XCNT(b.x)], 1u);
;     return b;
; }
; __global__ void __launch_bounds__(512) mega_fwd(Params P_) {
;     ...
;     if (threadIdx.x < 16) ((LAS unsigned*)(lds + LDS_BYTES - 64))[threadIdx.x] = 0u;
;     __syncthreads();
;     const XcdBarrier xbar = xcd_barrier_post((unsigned*)(P_.ws + 65536), (volatile LAS unsigned*)(lds + LDS_BYTES - 64));
_Z8mega_fwd6Params:
	s_load_dwordx4 s[28:31], s[0:1], 0xa8
	s_add_u32 s6, s0, 0xb0
	v_and_b32_e32 v204, 0x3ff, v0
	s_addc_u32 s7, s1, 0
	v_cmp_gt_u32_e32 vcc, 16, v204
	v_lshl_add_u32 v40, v204, 2, 0
	s_and_saveexec_b64 s[4:5], vcc
	v_add_u32_e32 v1, 0x243c0, v40
	v_mov_b32_e32 v2, 0
	ds_write_b32 v1, v2
	s_or_b64 exec, exec, s[4:5]
	s_waitcnt lgkmcnt(0)
	s_barrier
	s_add_u32 s96, s28, 0x10000
	s_getreg_b32 s3, hwreg(HW_REG_XCC_ID, 0, 4)
	s_addc_u32 s97, s29, 0
	s_and_b32 s75, s3, 15
	v_cmp_eq_u32_e64 s[4:5], 0, v204
	s_mov_b64 s[8:9], exec
	s_nop 0
	v_writelane_b32 v248, s4, 0
	s_nop 1
	v_writelane_b32 v248, s5, 1
	s_and_b64 s[4:5], s[8:9], s[4:5]
	s_mov_b64 exec, s[4:5]
	s_cbranch_execz .LBB0_5
	s_mov_b64 s[10:11], exec
	v_mbcnt_lo_u32_b32 v1, s10, 0
	v_mbcnt_hi_u32_b32 v1, s11, v1
	v_cmp_eq_u32_e32 vcc, 0, v1
	s_and_b64 s[4:5], exec, vcc
	s_mov_b64 exec, s[4:5]
	s_cbranch_execz .LBB0_5
	s_lshl_b32 s3, s75, 8
	s_bcnt1_i32_b64 s4, s[10:11]
	v_mov_b32_e32 v1, s3
	v_mov_b32_e32 v2, s4
	global_atomic_add v1, v2, s[96:97] offset:1024
	s_and_b32 s100, s2, 7
	s_lshl_b32 s100, s100, 2
	s_add_i32 s100, s100, 0x4000
	s_lshl_b32 s101, 1, s75
	v_mov_b32_e32 v4, s100
	v_mov_b32_e32 v5, s101
	global_atomic_or v4, v5, s[96:97]

; #define LAS __attribute__((address_space(3)))
; #define GAS __attribute__((address_space(1)))
; #define PP (opaque_params())
; __device__ __forceinline__ void xcd_barrier(const XcdBarrier& b) {
;     ...
;     __syncthreads();
; }
; __global__ void __launch_bounds__(512) mega_fwd(Params P_) {
;     ...
;     {   LAS float* gtab = (LAS float*)(lds + 131072);
;         if (threadIdx.x < 128) gtab[threadIdx.x] = (threadIdx.x < 64) ? ((const GAS float*)PP->in[4])[threadIdx.x] : ((const GAS float*)PP->in[5])[threadIdx.x - 64];
.LBB0_128:
	s_or_b64 exec, exec, s[6:7]
	s_add_u32 s100, s96, 0x4000
	s_addc_u32 s101, s97, 0
	v_mbcnt_lo_u32_b32 v4, -1, 0
	v_mbcnt_hi_u32_b32 v4, -1, v4
	v_and_b32_e32 v4, 7, v4
	v_lshlrev_b32_e32 v4, 2, v4
	global_load_dword v5, v4, s[100:101] sc1
	s_waitcnt vmcnt(0)
	v_bcnt_u32_b32 v5, v5, 0
	v_cmp_ne_u32_e32 vcc, 1, v5
	s_nop 3
	s_cmp_eq_u64 vcc, 0
	s_cselect_b32 s99, 1, 0
	s_movk_i32 s4, 0x80
	v_cmp_gt_u32_e32 vcc, s4, v204
	s_waitcnt lgkmcnt(0)
	s_barrier
	s_and_saveexec_b64 s[6:7], vcc
	s_cbranch_execz .LBB0_134
	v_cmp_lt_u32_e32 vcc, 63, v204
	v_mov_b32_e32 v1, 0
	v_lshlrev_b32_e32 v0, 2, v204
	s_and_saveexec_b64 s[4:5], vcc
	s_xor_b64 s[8:9], exec, s[4:5]
	s_cbranch_execz .LBB0_131
	s_mov_b64 s[4:5], s[0:1]
	s_load_dwordx2 s[4:5], s[4:5], 0x28
	s_waitcnt lgkmcnt(0)
	v_lshl_add_u64 v[0:1], s[4:5], 0, v[0:1]
	s_movk_i32 s4, 0xff00
	s_mov_b32 s5, -1
	v_lshl_add_u64 v[2:3], v[0:1], 0, s[4:5]

; __device__ __forceinline__ unsigned xb_ld(unsigned* p)              { return __hip_atomic_load(p, __ATOMIC_RELAXED, __HIP_MEMORY_SCOPE_AGENT); }
; __device__ __forceinline__ unsigned xb_add(unsigned* p, unsigned v) { return __hip_atomic_fetch_add(p, v, __ATOMIC_RELAXED, __HIP_MEMORY_SCOPE_AGENT); }
; #define XB_SPIN(cond, bar) do { unsigned _sp = 0; while (cond) { __builtin_amdgcn_s_sleep(1); \
;     if ((++_sp & 255u) == 0u) { if (xb_ld(&(bar)[XB_TMO])) break; if (_sp > XB_SPIN_CAP) { atomicAdd(&(bar)[XB_TMO], 1u); break; } } } } while (0)
; __device__ __forceinline__ void xcd_barrier(const XcdBarrier& b) {
;     ...
;         const unsigned old = xb_add(&bar[XB_XSUB(b.x)], 1u);
;         const unsigned gen = old / nloc;
;         if (old + 1u == (gen + 1u) * nloc) {
;             __builtin_amdgcn_fence(__ATOMIC_RELEASE, "agent");
;             asm volatile("s_waitcnt vmcnt(0)" ::: "memory");
;             const unsigned og = xb_add(&bar[XB_TOP], 1u);
;             const unsigned tg = og / nx;
;             if (og + 1u == (tg + 1u) * nx) xb_add(&bar[XB_TOPGEN], 1u);
;             else XB_SPIN(xb_ld(&bar[XB_TOPGEN]) == tg, bar);
;             __builtin_amdgcn_fence(__ATOMIC_ACQUIRE, "agent");
;             xb_add(&bar[XB_XGEN(b.x)], 1u);
.LBB0_855:
	s_andn2_saveexec_b64 s[4:5], s[14:15]
	s_cbranch_execz .LBB0_875
	s_mov_b64 s[14:15], exec
	s_waitcnt lgkmcnt(0)
	s_cmp_lg_u32 s99, 0
	s_cbranch_scc1 .LBB0_872
	buffer_wbl2 sc1
	s_waitcnt lgkmcnt(0)
	s_waitcnt vmcnt(0)
	v_mbcnt_lo_u32_b32 v1, s14, 0
	v_mbcnt_hi_u32_b32 v1, s15, v1
	v_cmp_eq_u32_e32 vcc, 0, v1
	s_and_saveexec_b64 s[16:17], vcc
	s_cbranch_execz .LBB0_858
	s_bcnt1_i32_b64 s4, s[14:15]
	v_mov_b32_e32 v2, 0x13000
	v_mov_b32_e32 v3, s4
	global_atomic_add v2, v2, v3, s[28:29] offset:1024 sc0

; __device__ __forceinline__ unsigned xb_ld(unsigned* p)              { return __hip_atomic_load(p, __ATOMIC_RELAXED, __HIP_MEMORY_SCOPE_AGENT); }
; __device__ __forceinline__ unsigned xb_add(unsigned* p, unsigned v) { return __hip_atomic_fetch_add(p, v, __ATOMIC_RELAXED, __HIP_MEMORY_SCOPE_AGENT); }
; #define XB_SPIN(cond, bar) do { unsigned _sp = 0; while (cond) { __builtin_amdgcn_s_sleep(1); \
;     if ((++_sp & 255u) == 0u) { if (xb_ld(&(bar)[XB_TMO])) break; if (_sp > XB_SPIN_CAP) { atomicAdd(&(bar)[XB_TMO], 1u); break; } } } } while (0)
; __device__ __forceinline__ void xcd_barrier(const XcdBarrier& b) {
;     ...
;         const unsigned old = xb_add(&bar[XB_XSUB(b.x)], 1u);
;         const unsigned gen = old / nloc;
;         if (old + 1u == (gen + 1u) * nloc) {
;             __builtin_amdgcn_fence(__ATOMIC_RELEASE, "agent");
;             asm volatile("s_waitcnt vmcnt(0)" ::: "memory");
;             const unsigned og = xb_add(&bar[XB_TOP], 1u);
;             const unsigned tg = og / nx;
;             if (og + 1u == (tg + 1u) * nx) xb_add(&bar[XB_TOPGEN], 1u);
;             else XB_SPIN(xb_ld(&bar[XB_TOPGEN]) == tg, bar);
;             __builtin_amdgcn_fence(__ATOMIC_ACQUIRE, "agent");
;             xb_add(&bar[XB_XGEN(b.x)], 1u);
.LBB0_954:
	s_andn2_saveexec_b64 s[4:5], s[14:15]
	s_cbranch_execz .LBB0_974
	s_mov_b64 s[14:15], exec
	s_waitcnt lgkmcnt(0)
	s_cmp_lg_u32 s99, 0
	s_cbranch_scc1 .LBB0_971
	buffer_wbl2 sc1
	s_waitcnt lgkmcnt(0)
	s_waitcnt vmcnt(0)
	v_mbcnt_lo_u32_b32 v1, s14, 0
	v_mbcnt_hi_u32_b32 v1, s15, v1
	v_cmp_eq_u32_e32 vcc, 0, v1
	s_and_saveexec_b64 s[18:19], vcc
	s_cbranch_execz .LBB0_957
	s_bcnt1_i32_b64 s4, s[14:15]
	v_mov_b32_e32 v2, 0x13000
	v_mov_b32_e32 v3, s4
	global_atomic_add v2, v2, v3, s[28:29] offset:1024 sc0

; __device__ __forceinline__ unsigned xb_ld(unsigned* p)              { return __hip_atomic_load(p, __ATOMIC_RELAXED, __HIP_MEMORY_SCOPE_AGENT); }
; __device__ __forceinline__ unsigned xb_add(unsigned* p, unsigned v) { return __hip_atomic_fetch_add(p, v, __ATOMIC_RELAXED, __HIP_MEMORY_SCOPE_AGENT); }
; #define XB_SPIN(cond, bar) do { unsigned _sp = 0; while (cond) { __builtin_amdgcn_s_sleep(1); \
;     if ((++_sp & 255u) == 0u) { if (xb_ld(&(bar)[XB_TMO])) break; if (_sp > XB_SPIN_CAP) { atomicAdd(&(bar)[XB_TMO], 1u); break; } } } } while (0)
; __device__ __forceinline__ void xcd_barrier(const XcdBarrier& b) {
;     ...
;         const unsigned old = xb_add(&bar[XB_XSUB(b.x)], 1u);
;         const unsigned gen = old / nloc;
;         if (old + 1u == (gen + 1u) * nloc) {
;             __builtin_amdgcn_fence(__ATOMIC_RELEASE, "agent");
;             asm volatile("s_waitcnt vmcnt(0)" ::: "memory");
;             const unsigned og = xb_add(&bar[XB_TOP], 1u);
;             const unsigned tg = og / nx;
;             if (og + 1u == (tg + 1u) * nx) xb_add(&bar[XB_TOPGEN], 1u);
;             else XB_SPIN(xb_ld(&bar[XB_TOPGEN]) == tg, bar);
;             __builtin_amdgcn_fence(__ATOMIC_ACQUIRE, "agent");
;             xb_add(&bar[XB_XGEN(b.x)], 1u);
.LBB0_1156:
	s_andn2_saveexec_b64 s[12:13], s[12:13]
	s_cbranch_execz .LBB0_1176
	s_mov_b64 s[12:13], exec
	s_waitcnt lgkmcnt(0)
	s_cmp_lg_u32 s99, 0
	s_cbranch_scc1 .LBB0_1173
	buffer_wbl2 sc1
	s_waitcnt lgkmcnt(0)
	s_waitcnt vmcnt(0)
	v_mbcnt_lo_u32_b32 v1, s12, 0
	v_mbcnt_hi_u32_b32 v1, s13, v1
	v_cmp_eq_u32_e32 vcc, 0, v1
	s_and_saveexec_b64 s[14:15], vcc
	s_cbranch_execz .LBB0_1159
	s_bcnt1_i32_b64 s12, s[12:13]
	v_mov_b32_e32 v2, 0x13000
	v_mov_b32_e32 v3, s12
	global_atomic_add v2, v2, v3, s[28:29] offset:1024 sc0

; __global__ void __launch_bounds__(512) mega_fwd(Params P_) {
	.amdhsa_kernel _Z8mega_fwd6Params
		.amdhsa_group_segment_fixed_size 0
		.amdhsa_private_segment_fixed_size 0
		.amdhsa_kernarg_size 432
		.amdhsa_user_sgpr_count 2
		.amdhsa_user_sgpr_dispatch_ptr 0
		.amdhsa_user_sgpr_queue_ptr 0
		.amdhsa_user_sgpr_kernarg_segment_ptr 1
		.amdhsa_user_sgpr_dispatch_id 0
		.amdhsa_user_sgpr_kernarg_preload_length 0
		.amdhsa_user_sgpr_kernarg_preload_offset 0
		.amdhsa_user_sgpr_private_segment_size 0
		.amdhsa_uses_dynamic_stack 0
		.amdhsa_enable_private_segment 0
		.amdhsa_system_sgpr_workgroup_id_x 1
		.amdhsa_system_sgpr_workgroup_id_y 0
		.amdhsa_system_sgpr_workgroup_id_z 0
		.amdhsa_system_sgpr_workgroup_info 0
		.amdhsa_system_vgpr_workitem_id 2
		.amdhsa_next_free_vgpr 249
		.amdhsa_next_free_sgpr 102
		.amdhsa_accum_offset 252
		.amdhsa_reserve_vcc 1
		.amdhsa_float_round_mode_32 0
		.amdhsa_float_round_mode_16_64 0
		.amdhsa_float_denorm_mode_32 3
		.amdhsa_float_denorm_mode_16_64 3
		.amdhsa_dx10_clamp 1
		.amdhsa_ieee_mode 1
		.amdhsa_fp16_overflow 0
		.amdhsa_tg_split 0
		.amdhsa_exception_fp_ieee_invalid_op 0
		.amdhsa_exception_fp_denorm_src 0
		.amdhsa_exception_fp_ieee_div_zero 0
		.amdhsa_exception_fp_ieee_overflow 0
		.amdhsa_exception_fp_ieee_underflow 0
		.amdhsa_exception_fp_ieee_inexact 0
		.amdhsa_exception_int_div_zero 0
	.end_amdhsa_kernel

; __global__ void __launch_bounds__(512) mega_fwd(Params P_) {
amdhsa.kernels:
  - .agpr_count:     0
    .args:
      - .offset:         0
        .size:           176
        .value_kind:     by_value
      - .offset:         176
        .size:           4
        .value_kind:     hidden_block_count_x
      - .offset:         180
        .size:           4
        .value_kind:     hidden_block_count_y
      - .offset:         184
        .size:           4
        .value_kind:     hidden_block_count_z
      - .offset:         188
        .size:           2
        .value_kind:     hidden_group_size_x
      - .offset:         190
        .size:           2
        .value_kind:     hidden_group_size_y
      - .offset:         192
        .size:           2
        .value_kind:     hidden_group_size_z
      - .offset:         194
        .size:           2
        .value_kind:     hidden_remainder_x
      - .offset:         196
        .size:           2
        .value_kind:     hidden_remainder_y
      - .offset:         198
        .size:           2
        .value_kind:     hidden_remainder_z
      - .offset:         216
        .size:           8
        .value_kind:     hidden_global_offset_x
      - .offset:         224
        .size:           8
        .value_kind:     hidden_global_offset_y
      - .offset:         232
        .size:           8
        .value_kind:     hidden_global_offset_z
      - .offset:         240
        .size:           2
        .value_kind:     hidden_grid_dims
      - .offset:         264
        .size:           8
        .value_kind:     hidden_multigrid_sync_arg
      - .offset:         296
        .size:           4
        .value_kind:     hidden_dynamic_lds_size
    .group_segment_fixed_size: 0
    .kernarg_segment_align: 8
    .kernarg_segment_size: 432
    .language:       OpenCL C
    .language_version:
      - 2
      - 0
    .max_flat_workgroup_size: 512
    .name:           _Z8mega_fwd6Params
    .private_segment_fixed_size: 0
    .sgpr_count:     108
    .sgpr_spill_count: 14
    .symbol:         _Z8mega_fwd6Params.kd
    .uniform_work_group_size: 1
    .uses_dynamic_stack: false
    .vgpr_count:     249
    .vgpr_spill_count: 0
    .wavefront_size: 64
